# adds: P4 stores the bf16 copy of x1 before the second row-statistics exchange (drains under the exchange latency)
# baseline (speedup 1.0000x reference)
.LBB0_645:
	s_or_b64 exec, exec, s[12:13]
	s_lshl_b32 s82, s14, 19
	s_lshl_b32 s83, s16, 9
	s_add_u32 s86, s22, s82
	s_addc_u32 s87, s23, 0
	s_add_u32 s86, s86, s83
	s_addc_u32 s87, s87, 0
	v_and_b32_e32 v248, 15, v1
	s_lshr_b32 s82, s48, 2
	s_lshl_b32 s82, s82, 6
	v_lshrrev_b32_e32 v249, 4, v1
	v_add_u32_e32 v248, s82, v248
	s_and_b32 s83, s48, 3
	v_lshlrev_b32_e32 v249, 4, v249
	s_lshl_b32 s83, s83, 6
	v_lshlrev_b32_e32 v248, 11, v248
	v_add3_u32 v248, v248, v249, s83
	v_cvt_pk_bf16_f32 v236, v126, v127
	v_cvt_pk_bf16_f32 v237, v128, v129
	v_cvt_pk_bf16_f32 v238, v122, v123
	v_cvt_pk_bf16_f32 v239, v124, v125
	s_add_u32 s84, s86, 0x0
	s_addc_u32 s85, s87, 0
	global_store_dwordx4 v248, v[236:239], s[84:85] sc1
	s_nop 1
	v_cvt_pk_bf16_f32 v240, v118, v119
	v_cvt_pk_bf16_f32 v241, v120, v121
	v_cvt_pk_bf16_f32 v242, v114, v115
	v_cvt_pk_bf16_f32 v243, v116, v117
	s_add_u32 s84, s86, 0x100
	s_addc_u32 s85, s87, 0
	global_store_dwordx4 v248, v[240:243], s[84:85] sc1
	s_nop 1
	v_cvt_pk_bf16_f32 v236, v110, v111
	v_cvt_pk_bf16_f32 v237, v112, v113
	v_cvt_pk_bf16_f32 v238, v106, v107
	v_cvt_pk_bf16_f32 v239, v108, v109
	s_add_u32 s84, s86, 0x8000
	s_addc_u32 s85, s87, 0
	global_store_dwordx4 v248, v[236:239], s[84:85] sc1
	s_nop 1
	v_cvt_pk_bf16_f32 v240, v102, v103
	v_cvt_pk_bf16_f32 v241, v104, v105
	v_cvt_pk_bf16_f32 v242, v98, v99
	v_cvt_pk_bf16_f32 v243, v100, v101
	s_add_u32 s84, s86, 0x8100
	s_addc_u32 s85, s87, 0
	global_store_dwordx4 v248, v[240:243], s[84:85] sc1
	s_nop 1
	v_cvt_pk_bf16_f32 v236, v94, v95
	v_cvt_pk_bf16_f32 v237, v96, v97
	v_cvt_pk_bf16_f32 v238, v90, v91
	v_cvt_pk_bf16_f32 v239, v92, v93
	s_add_u32 s84, s86, 0x10000
	s_addc_u32 s85, s87, 0
	global_store_dwordx4 v248, v[236:239], s[84:85] sc1
	s_nop 1
	v_cvt_pk_bf16_f32 v240, v86, v87
	v_cvt_pk_bf16_f32 v241, v88, v89
	v_cvt_pk_bf16_f32 v242, v82, v83
	v_cvt_pk_bf16_f32 v243, v84, v85
	s_add_u32 s84, s86, 0x10100
	s_addc_u32 s85, s87, 0
	global_store_dwordx4 v248, v[240:243], s[84:85] sc1
	s_nop 1
	v_cvt_pk_bf16_f32 v236, v78, v79
	v_cvt_pk_bf16_f32 v237, v80, v81
	v_cvt_pk_bf16_f32 v238, v74, v75
	v_cvt_pk_bf16_f32 v239, v76, v77
	s_add_u32 s84, s86, 0x18000
	s_addc_u32 s85, s87, 0
	global_store_dwordx4 v248, v[236:239], s[84:85] sc1
	s_nop 1
	v_cvt_pk_bf16_f32 v240, v70, v71
	v_cvt_pk_bf16_f32 v241, v72, v73
	v_cvt_pk_bf16_f32 v242, v66, v67
	v_cvt_pk_bf16_f32 v243, v68, v69
	s_add_u32 s84, s86, 0x18100
	s_addc_u32 s85, s87, 0
	global_store_dwordx4 v248, v[240:243], s[84:85] sc1
	s_nop 1
	v_cvt_pk_bf16_f32 v236, v62, v63
	v_cvt_pk_bf16_f32 v237, v64, v65
	v_cvt_pk_bf16_f32 v238, v58, v59
	v_cvt_pk_bf16_f32 v239, v60, v61
	s_add_u32 s84, s86, 0x40000
	s_addc_u32 s85, s87, 0
	global_store_dwordx4 v248, v[236:239], s[84:85] sc1
	s_nop 1
	v_cvt_pk_bf16_f32 v240, v54, v55
	v_cvt_pk_bf16_f32 v241, v56, v57
	v_cvt_pk_bf16_f32 v242, v50, v51
	v_cvt_pk_bf16_f32 v243, v52, v53
	s_add_u32 s84, s86, 0x40100
	s_addc_u32 s85, s87, 0
	global_store_dwordx4 v248, v[240:243], s[84:85] sc1
	s_nop 1
	v_cvt_pk_bf16_f32 v236, v46, v47
	v_cvt_pk_bf16_f32 v237, v48, v49
	v_cvt_pk_bf16_f32 v238, v42, v43
	v_cvt_pk_bf16_f32 v239, v44, v45
	s_add_u32 s84, s86, 0x48000
	s_addc_u32 s85, s87, 0
	global_store_dwordx4 v248, v[236:239], s[84:85] sc1
	s_nop 1
	v_cvt_pk_bf16_f32 v240, v38, v39
	v_cvt_pk_bf16_f32 v241, v40, v41
	v_cvt_pk_bf16_f32 v242, v34, v35
	v_cvt_pk_bf16_f32 v243, v36, v37
	s_add_u32 s84, s86, 0x48100
	s_addc_u32 s85, s87, 0
	global_store_dwordx4 v248, v[240:243], s[84:85] sc1
	s_nop 1
	v_cvt_pk_bf16_f32 v236, v30, v31
	v_cvt_pk_bf16_f32 v237, v32, v33
	v_cvt_pk_bf16_f32 v238, v26, v27
	v_cvt_pk_bf16_f32 v239, v28, v29
	s_add_u32 s84, s86, 0x50000
	s_addc_u32 s85, s87, 0
	global_store_dwordx4 v248, v[236:239], s[84:85] sc1
	s_nop 1
	v_cvt_pk_bf16_f32 v240, v22, v23
	v_cvt_pk_bf16_f32 v241, v24, v25
	v_cvt_pk_bf16_f32 v242, v18, v19
	v_cvt_pk_bf16_f32 v243, v20, v21
	s_add_u32 s84, s86, 0x50100
	s_addc_u32 s85, s87, 0
	global_store_dwordx4 v248, v[240:243], s[84:85] sc1
	s_nop 1
	v_cvt_pk_bf16_f32 v236, v14, v15
	v_cvt_pk_bf16_f32 v237, v16, v17
	v_cvt_pk_bf16_f32 v238, v10, v11
	v_cvt_pk_bf16_f32 v239, v12, v13
	s_add_u32 s84, s86, 0x58000
	s_addc_u32 s85, s87, 0
	global_store_dwordx4 v248, v[236:239], s[84:85] sc1
	s_nop 1
	v_cvt_pk_bf16_f32 v240, v6, v7
	v_cvt_pk_bf16_f32 v241, v8, v9
	v_cvt_pk_bf16_f32 v242, v2, v3
	v_cvt_pk_bf16_f32 v243, v4, v5
	s_add_u32 s84, s86, 0x58100
	s_addc_u32 s85, s87, 0
	global_store_dwordx4 v248, v[240:243], s[84:85] sc1
	s_nop 1
	s_waitcnt lgkmcnt(0)
	s_barrier
	s_add_u32 s6, s34, 0x1b40000
	s_addc_u32 s7, s35, 0
	s_and_saveexec_b64 s[12:13], s[8:9]
	s_cbranch_execz .LBB0_647
	s_waitcnt lgkmcnt(0)
	ds_read_b128 v[130:133], v223
	s_ashr_i32 s17, s16, 31
	v_lshl_add_u64 v[134:135], v[212:213], 4, s[6:7]
	s_waitcnt lgkmcnt(0)
	v_mov_b32_e32 v136, v131
	v_mov_b32_e32 v137, v132
	v_mov_b32_e32 v131, v133
	v_pk_add_f32 v[130:131], v[136:137], v[130:131]
	v_lshl_add_u64 v[132:133], s[16:17], 2, v[134:135]
	v_pk_add_f32 v[130:131], v[130:131], v[130:131] op_sel:[0,1] op_sel_hi:[1,0]
	global_store_dword v[132:133], v130, off sc1

.LBB0_670:
	v_add_u32_e32 v162, s40, v217
	v_ashrrev_i32_e32 v163, 31, v162
	v_lshlrev_b64 v[168:169], 10, v[162:163]
	v_lshl_add_u64 v[172:173], v[168:169], 0, v[210:211]
	v_cvt_pk_bf16_f32 v168, v126, v127
	s_waitcnt lgkmcnt(0)
	v_pk_mul_f32 v[126:127], v[126:127], v[166:167] op_sel_hi:[1,0]
	v_cvt_pk_bf16_f32 v169, v128, v129
	v_cvt_pk_bf16_f32 v170, v122, v123
	v_pk_mul_f32 v[128:129], v[128:129], v[166:167] op_sel_hi:[1,0]
	s_waitcnt vmcnt(3)
	v_pk_fma_f32 v[126:127], v[154:155], v[126:127], v[158:159]
	v_pk_mul_f32 v[122:123], v[122:123], v[166:167] op_sel_hi:[1,0]
	v_cvt_pk_bf16_f32 v171, v124, v125
	v_pk_fma_f32 v[128:129], v[156:157], v[128:129], v[160:161]
	v_pk_mul_f32 v[124:125], v[124:125], v[166:167] op_sel_hi:[1,0]
	v_pk_fma_f32 v[174:175], v[146:147], v[122:123], v[150:151]
	v_cvt_pk_bf16_f32 v122, v126, v127
	v_lshlrev_b64 v[126:127], 1, v[172:173]
	v_pk_fma_f32 v[176:177], v[148:149], v[124:125], v[152:153]
	v_cvt_pk_bf16_f32 v123, v128, v129
	v_cvt_pk_bf16_f32 v124, v174, v175
	v_lshl_add_u64 v[128:129], s[22:23], 0, v[126:127]
	v_cvt_pk_bf16_f32 v125, v176, v177
	v_lshl_add_u64 v[126:127], s[24:25], 0, v[126:127]
	global_store_dwordx4 v[126:127], v[122:125], off sc1
	s_nop 1
	v_cvt_pk_bf16_f32 v122, v118, v119
	v_pk_mul_f32 v[118:119], v[118:119], v[166:167] op_sel_hi:[1,0]
	v_cvt_pk_bf16_f32 v123, v120, v121
	v_cvt_pk_bf16_f32 v124, v114, v115
	v_cvt_pk_bf16_f32 v125, v116, v117
	v_pk_mul_f32 v[120:121], v[120:121], v[166:167] op_sel_hi:[1,0]
	s_waitcnt vmcnt(2)
	v_pk_fma_f32 v[118:119], v[134:135], v[118:119], v[142:143]
	v_pk_mul_f32 v[116:117], v[116:117], v[166:167] op_sel_hi:[1,0]
	v_pk_mul_f32 v[114:115], v[114:115], v[166:167] op_sel_hi:[1,0]
	s_mov_b64 s[10:11], 0x100
	v_pk_fma_f32 v[120:121], v[136:137], v[120:121], v[144:145]
	s_waitcnt vmcnt(0)
	v_pk_fma_f32 v[166:167], v[130:131], v[114:115], v[138:139]
	v_pk_fma_f32 v[168:169], v[132:133], v[116:117], v[140:141]
	v_cvt_pk_bf16_f32 v114, v118, v119
	v_cvt_pk_bf16_f32 v115, v120, v121
	v_cvt_pk_bf16_f32 v116, v166, v167
	v_lshl_add_u64 v[118:119], v[128:129], 0, s[10:11]
	v_cvt_pk_bf16_f32 v117, v168, v169
	v_lshl_add_u64 v[118:119], v[126:127], 0, s[10:11]
	global_store_dwordx4 v[118:119], v[114:117], off sc1
	s_nop 1
	v_cndmask_b32_e64 v114, 0, 1, s[8:9]
	v_cmp_ne_u32_e64 s[6:7], 1, v114
	s_andn2_b64 vcc, exec, s[8:9]
	s_cbranch_vccnz .LBB0_672
	ds_read_b32 v164, v165 offset:8256
.LBB0_672:
	v_add3_u32 v114, s40, v217, 16
	v_ashrrev_i32_e32 v115, 31, v114
	v_lshlrev_b64 v[114:115], 10, v[114:115]
	v_lshl_add_u64 v[118:119], v[114:115], 0, v[210:211]
	v_cvt_pk_bf16_f32 v114, v110, v111
	s_waitcnt lgkmcnt(0)
	v_pk_mul_f32 v[110:111], v[110:111], v[164:165] op_sel_hi:[1,0]
	v_cvt_pk_bf16_f32 v115, v112, v113
	v_cvt_pk_bf16_f32 v116, v106, v107
	v_cvt_pk_bf16_f32 v117, v108, v109
	v_pk_mul_f32 v[112:113], v[112:113], v[164:165] op_sel_hi:[1,0]
	v_pk_fma_f32 v[110:111], v[154:155], v[110:111], v[158:159]
	v_pk_mul_f32 v[108:109], v[108:109], v[164:165] op_sel_hi:[1,0]
	v_pk_mul_f32 v[106:107], v[106:107], v[164:165] op_sel_hi:[1,0]
	v_pk_fma_f32 v[112:113], v[156:157], v[112:113], v[160:161]
	v_pk_fma_f32 v[120:121], v[148:149], v[108:109], v[152:153]
	v_pk_fma_f32 v[108:109], v[146:147], v[106:107], v[150:151]
	v_cvt_pk_bf16_f32 v106, v110, v111
	v_lshlrev_b64 v[110:111], 1, v[118:119]
	v_cvt_pk_bf16_f32 v107, v112, v113
	v_cvt_pk_bf16_f32 v108, v108, v109
	v_cvt_pk_bf16_f32 v109, v120, v121
	v_lshl_add_u64 v[112:113], s[22:23], 0, v[110:111]
	v_lshl_add_u64 v[110:111], s[24:25], 0, v[110:111]
	global_store_dwordx4 v[110:111], v[106:109], off sc1
	s_nop 1
	v_cvt_pk_bf16_f32 v106, v102, v103
	v_cvt_pk_bf16_f32 v107, v104, v105
	v_cvt_pk_bf16_f32 v108, v98, v99
	v_cvt_pk_bf16_f32 v109, v100, v101
	v_pk_mul_f32 v[102:103], v[102:103], v[164:165] op_sel_hi:[1,0]
	v_pk_mul_f32 v[100:101], v[100:101], v[164:165] op_sel_hi:[1,0]
	v_pk_mul_f32 v[98:99], v[98:99], v[164:165] op_sel_hi:[1,0]
	v_pk_mul_f32 v[104:105], v[104:105], v[164:165] op_sel_hi:[1,0]
	v_pk_fma_f32 v[102:103], v[134:135], v[102:103], v[142:143]
	v_pk_fma_f32 v[114:115], v[132:133], v[100:101], v[140:141]
	v_pk_fma_f32 v[100:101], v[130:131], v[98:99], v[138:139]
	v_pk_fma_f32 v[104:105], v[136:137], v[104:105], v[144:145]
	v_cvt_pk_bf16_f32 v98, v102, v103
	v_lshl_add_u64 v[102:103], v[112:113], 0, s[10:11]
	v_cvt_pk_bf16_f32 v99, v104, v105
	v_cvt_pk_bf16_f32 v100, v100, v101
	v_cvt_pk_bf16_f32 v101, v114, v115
	v_lshl_add_u64 v[102:103], v[110:111], 0, s[10:11]
	global_store_dwordx4 v[102:103], v[98:101], off sc1
	s_nop 1
	v_mov_b32_e32 v98, 0x7fc00000
	s_and_b64 vcc, exec, s[6:7]
	v_mov_b32_e32 v100, 0x7fc00000
	s_cbranch_vccnz .LBB0_674
	ds_read_b32 v100, v165 offset:8320
.LBB0_674:
	v_add3_u32 v102, s40, v217, 32
	v_ashrrev_i32_e32 v103, 31, v102
	v_lshlrev_b64 v[102:103], 10, v[102:103]
	v_lshl_add_u64 v[106:107], v[102:103], 0, v[210:211]
	v_cvt_pk_bf16_f32 v102, v94, v95
	s_waitcnt lgkmcnt(0)
	v_pk_mul_f32 v[94:95], v[94:95], v[100:101] op_sel_hi:[1,0]
	v_cvt_pk_bf16_f32 v103, v96, v97
	v_cvt_pk_bf16_f32 v104, v90, v91
	v_cvt_pk_bf16_f32 v105, v92, v93
	v_pk_mul_f32 v[96:97], v[96:97], v[100:101] op_sel_hi:[1,0]
	v_pk_fma_f32 v[94:95], v[154:155], v[94:95], v[158:159]
	v_pk_mul_f32 v[92:93], v[92:93], v[100:101] op_sel_hi:[1,0]
	v_pk_mul_f32 v[90:91], v[90:91], v[100:101] op_sel_hi:[1,0]
	v_pk_fma_f32 v[96:97], v[156:157], v[96:97], v[160:161]
	v_pk_fma_f32 v[108:109], v[148:149], v[92:93], v[152:153]
	v_pk_fma_f32 v[92:93], v[146:147], v[90:91], v[150:151]
	v_cvt_pk_bf16_f32 v90, v94, v95
	v_lshlrev_b64 v[94:95], 1, v[106:107]
	v_cvt_pk_bf16_f32 v91, v96, v97
	v_cvt_pk_bf16_f32 v92, v92, v93
	v_cvt_pk_bf16_f32 v93, v108, v109
	v_lshl_add_u64 v[96:97], s[22:23], 0, v[94:95]
	v_lshl_add_u64 v[94:95], s[24:25], 0, v[94:95]
	global_store_dwordx4 v[94:95], v[90:93], off sc1
	s_nop 1
	v_cvt_pk_bf16_f32 v90, v86, v87
	v_cvt_pk_bf16_f32 v91, v88, v89
	v_cvt_pk_bf16_f32 v92, v82, v83
	v_cvt_pk_bf16_f32 v93, v84, v85
	v_pk_mul_f32 v[86:87], v[86:87], v[100:101] op_sel_hi:[1,0]
	v_pk_mul_f32 v[84:85], v[84:85], v[100:101] op_sel_hi:[1,0]
	v_pk_mul_f32 v[82:83], v[82:83], v[100:101] op_sel_hi:[1,0]
	v_pk_mul_f32 v[88:89], v[88:89], v[100:101] op_sel_hi:[1,0]
	v_pk_fma_f32 v[86:87], v[134:135], v[86:87], v[142:143]
	v_pk_fma_f32 v[100:101], v[132:133], v[84:85], v[140:141]
	v_pk_fma_f32 v[84:85], v[130:131], v[82:83], v[138:139]
	s_mov_b64 s[8:9], 0x100
	v_pk_fma_f32 v[88:89], v[136:137], v[88:89], v[144:145]
	v_cvt_pk_bf16_f32 v82, v86, v87
	v_lshl_add_u64 v[86:87], v[96:97], 0, s[8:9]
	v_cvt_pk_bf16_f32 v83, v88, v89
	v_cvt_pk_bf16_f32 v84, v84, v85
	v_cvt_pk_bf16_f32 v85, v100, v101
	v_lshl_add_u64 v[86:87], v[94:95], 0, s[8:9]
	global_store_dwordx4 v[86:87], v[82:85], off sc1
	s_nop 1
	s_and_b64 vcc, exec, s[6:7]
	s_cbranch_vccnz .LBB0_676
	ds_read_b32 v98, v165 offset:8384
.LBB0_676:
	v_add3_u32 v82, s40, v217, 48
	v_ashrrev_i32_e32 v83, 31, v82
	v_lshlrev_b64 v[82:83], 10, v[82:83]
	v_lshl_add_u64 v[86:87], v[82:83], 0, v[210:211]
	v_cvt_pk_bf16_f32 v82, v78, v79
	s_waitcnt lgkmcnt(0)
	v_pk_mul_f32 v[78:79], v[78:79], v[98:99] op_sel_hi:[1,0]
	v_cvt_pk_bf16_f32 v83, v80, v81
	v_cvt_pk_bf16_f32 v84, v74, v75
	v_cvt_pk_bf16_f32 v85, v76, v77
	v_pk_mul_f32 v[80:81], v[80:81], v[98:99] op_sel_hi:[1,0]
	v_pk_fma_f32 v[78:79], v[154:155], v[78:79], v[158:159]
	v_pk_mul_f32 v[76:77], v[76:77], v[98:99] op_sel_hi:[1,0]
	v_pk_mul_f32 v[74:75], v[74:75], v[98:99] op_sel_hi:[1,0]
	v_pk_fma_f32 v[80:81], v[156:157], v[80:81], v[160:161]
	v_pk_fma_f32 v[88:89], v[148:149], v[76:77], v[152:153]
	v_pk_fma_f32 v[76:77], v[146:147], v[74:75], v[150:151]
	v_cvt_pk_bf16_f32 v74, v78, v79
	v_lshlrev_b64 v[78:79], 1, v[86:87]
	v_cvt_pk_bf16_f32 v75, v80, v81
	v_cvt_pk_bf16_f32 v76, v76, v77
	v_cvt_pk_bf16_f32 v77, v88, v89
	v_lshl_add_u64 v[80:81], s[22:23], 0, v[78:79]
	v_lshl_add_u64 v[78:79], s[24:25], 0, v[78:79]
	global_store_dwordx4 v[78:79], v[74:77], off sc1
	s_nop 1
	v_cvt_pk_bf16_f32 v74, v70, v71
	v_cvt_pk_bf16_f32 v75, v72, v73
	v_cvt_pk_bf16_f32 v76, v66, v67
	v_cvt_pk_bf16_f32 v77, v68, v69
	v_pk_mul_f32 v[70:71], v[70:71], v[98:99] op_sel_hi:[1,0]
	v_pk_mul_f32 v[68:69], v[68:69], v[98:99] op_sel_hi:[1,0]
	v_pk_mul_f32 v[66:67], v[66:67], v[98:99] op_sel_hi:[1,0]
	v_pk_mul_f32 v[72:73], v[72:73], v[98:99] op_sel_hi:[1,0]
	v_pk_fma_f32 v[70:71], v[134:135], v[70:71], v[142:143]
	v_pk_fma_f32 v[82:83], v[132:133], v[68:69], v[140:141]
	v_pk_fma_f32 v[68:69], v[130:131], v[66:67], v[138:139]
	v_pk_fma_f32 v[72:73], v[136:137], v[72:73], v[144:145]
	v_cvt_pk_bf16_f32 v66, v70, v71
	v_lshl_add_u64 v[70:71], v[80:81], 0, s[8:9]
	v_cvt_pk_bf16_f32 v67, v72, v73
	v_cvt_pk_bf16_f32 v68, v68, v69
	v_cvt_pk_bf16_f32 v69, v82, v83
	v_lshl_add_u64 v[70:71], v[78:79], 0, s[8:9]
	global_store_dwordx4 v[70:71], v[66:69], off sc1
	s_nop 1
	v_mov_b32_e32 v66, 0x7fc00000
	s_and_b64 vcc, exec, s[6:7]
	v_mov_b32_e32 v68, 0x7fc00000
	s_cbranch_vccnz .LBB0_678
	ds_read_b32 v68, v165 offset:8704
.LBB0_678:
	v_add_u32_e32 v70, 0x80, v162
	v_ashrrev_i32_e32 v71, 31, v70
	v_lshlrev_b64 v[70:71], 10, v[70:71]
	v_lshl_add_u64 v[74:75], v[70:71], 0, v[210:211]
	v_cvt_pk_bf16_f32 v70, v62, v63
	s_waitcnt lgkmcnt(0)
	v_pk_mul_f32 v[62:63], v[62:63], v[68:69] op_sel_hi:[1,0]
	v_cvt_pk_bf16_f32 v71, v64, v65
	v_cvt_pk_bf16_f32 v72, v58, v59
	v_cvt_pk_bf16_f32 v73, v60, v61
	v_pk_mul_f32 v[64:65], v[64:65], v[68:69] op_sel_hi:[1,0]
	v_pk_fma_f32 v[62:63], v[154:155], v[62:63], v[158:159]
	v_pk_mul_f32 v[60:61], v[60:61], v[68:69] op_sel_hi:[1,0]
	v_pk_mul_f32 v[58:59], v[58:59], v[68:69] op_sel_hi:[1,0]
	v_pk_fma_f32 v[64:65], v[156:157], v[64:65], v[160:161]
	v_pk_fma_f32 v[76:77], v[148:149], v[60:61], v[152:153]
	v_pk_fma_f32 v[60:61], v[146:147], v[58:59], v[150:151]
	v_cvt_pk_bf16_f32 v58, v62, v63
	v_lshlrev_b64 v[62:63], 1, v[74:75]
	v_cvt_pk_bf16_f32 v59, v64, v65
	v_cvt_pk_bf16_f32 v60, v60, v61
	v_cvt_pk_bf16_f32 v61, v76, v77
	v_lshl_add_u64 v[64:65], s[22:23], 0, v[62:63]
	v_lshl_add_u64 v[62:63], s[24:25], 0, v[62:63]
	global_store_dwordx4 v[62:63], v[58:61], off sc1
	s_nop 1
	v_cvt_pk_bf16_f32 v58, v54, v55
	v_cvt_pk_bf16_f32 v59, v56, v57
	v_cvt_pk_bf16_f32 v60, v50, v51
	v_cvt_pk_bf16_f32 v61, v52, v53
	v_pk_mul_f32 v[54:55], v[54:55], v[68:69] op_sel_hi:[1,0]
	v_pk_mul_f32 v[52:53], v[52:53], v[68:69] op_sel_hi:[1,0]
	v_pk_mul_f32 v[50:51], v[50:51], v[68:69] op_sel_hi:[1,0]
	v_pk_mul_f32 v[56:57], v[56:57], v[68:69] op_sel_hi:[1,0]
	v_pk_fma_f32 v[54:55], v[134:135], v[54:55], v[142:143]
	v_pk_fma_f32 v[68:69], v[132:133], v[52:53], v[140:141]
	v_pk_fma_f32 v[52:53], v[130:131], v[50:51], v[138:139]
	v_pk_fma_f32 v[56:57], v[136:137], v[56:57], v[144:145]
	v_cvt_pk_bf16_f32 v50, v54, v55
	v_lshl_add_u64 v[54:55], v[64:65], 0, s[8:9]
	v_cvt_pk_bf16_f32 v51, v56, v57
	v_cvt_pk_bf16_f32 v52, v52, v53
	v_cvt_pk_bf16_f32 v53, v68, v69
	v_lshl_add_u64 v[54:55], v[62:63], 0, s[8:9]
	global_store_dwordx4 v[54:55], v[50:53], off sc1
	s_nop 1
	s_and_b64 vcc, exec, s[6:7]
	s_cbranch_vccnz .LBB0_680
	ds_read_b32 v66, v165 offset:8768
.LBB0_680:
	v_add_u32_e32 v50, 0x90, v162
	v_ashrrev_i32_e32 v51, 31, v50
	v_lshlrev_b64 v[50:51], 10, v[50:51]
	v_lshl_add_u64 v[54:55], v[50:51], 0, v[210:211]
	v_cvt_pk_bf16_f32 v50, v46, v47
	s_waitcnt lgkmcnt(0)
	v_pk_mul_f32 v[46:47], v[46:47], v[66:67] op_sel_hi:[1,0]
	v_cvt_pk_bf16_f32 v51, v48, v49
	v_cvt_pk_bf16_f32 v52, v42, v43
	v_cvt_pk_bf16_f32 v53, v44, v45
	v_pk_mul_f32 v[48:49], v[48:49], v[66:67] op_sel_hi:[1,0]
	v_pk_fma_f32 v[46:47], v[154:155], v[46:47], v[158:159]
	v_pk_mul_f32 v[44:45], v[44:45], v[66:67] op_sel_hi:[1,0]
	v_pk_mul_f32 v[42:43], v[42:43], v[66:67] op_sel_hi:[1,0]
	v_pk_fma_f32 v[48:49], v[156:157], v[48:49], v[160:161]
	v_pk_fma_f32 v[56:57], v[148:149], v[44:45], v[152:153]
	v_pk_fma_f32 v[44:45], v[146:147], v[42:43], v[150:151]
	v_cvt_pk_bf16_f32 v42, v46, v47
	v_lshlrev_b64 v[46:47], 1, v[54:55]
	v_cvt_pk_bf16_f32 v43, v48, v49
	v_cvt_pk_bf16_f32 v44, v44, v45
	v_cvt_pk_bf16_f32 v45, v56, v57
	v_lshl_add_u64 v[48:49], s[22:23], 0, v[46:47]
	v_lshl_add_u64 v[46:47], s[24:25], 0, v[46:47]
	global_store_dwordx4 v[46:47], v[42:45], off sc1
	s_nop 1
	v_cvt_pk_bf16_f32 v42, v38, v39
	v_cvt_pk_bf16_f32 v43, v40, v41
	v_cvt_pk_bf16_f32 v44, v34, v35
	v_cvt_pk_bf16_f32 v45, v36, v37
	v_pk_mul_f32 v[38:39], v[38:39], v[66:67] op_sel_hi:[1,0]
	v_pk_mul_f32 v[36:37], v[36:37], v[66:67] op_sel_hi:[1,0]
	v_pk_mul_f32 v[34:35], v[34:35], v[66:67] op_sel_hi:[1,0]
	v_pk_mul_f32 v[40:41], v[40:41], v[66:67] op_sel_hi:[1,0]
	v_pk_fma_f32 v[38:39], v[134:135], v[38:39], v[142:143]
	v_pk_fma_f32 v[50:51], v[132:133], v[36:37], v[140:141]
	v_pk_fma_f32 v[36:37], v[130:131], v[34:35], v[138:139]
	v_pk_fma_f32 v[40:41], v[136:137], v[40:41], v[144:145]
	v_cvt_pk_bf16_f32 v34, v38, v39
	v_lshl_add_u64 v[38:39], v[48:49], 0, s[8:9]
	v_cvt_pk_bf16_f32 v35, v40, v41
	v_cvt_pk_bf16_f32 v36, v36, v37
	v_cvt_pk_bf16_f32 v37, v50, v51
	v_lshl_add_u64 v[38:39], v[46:47], 0, s[8:9]
	global_store_dwordx4 v[38:39], v[34:37], off sc1
	s_nop 1
	v_mov_b32_e32 v34, 0x7fc00000
	s_and_b64 vcc, exec, s[6:7]
	v_mov_b32_e32 v36, 0x7fc00000
	s_cbranch_vccnz .LBB0_682
	ds_read_b32 v36, v165 offset:8832
.LBB0_682:
	v_add_u32_e32 v38, 0xa0, v162
	v_ashrrev_i32_e32 v39, 31, v38
	v_lshlrev_b64 v[38:39], 10, v[38:39]
	v_lshl_add_u64 v[42:43], v[38:39], 0, v[210:211]
	v_cvt_pk_bf16_f32 v38, v30, v31
	s_waitcnt lgkmcnt(0)
	v_pk_mul_f32 v[30:31], v[30:31], v[36:37] op_sel_hi:[1,0]
	v_cvt_pk_bf16_f32 v39, v32, v33
	v_cvt_pk_bf16_f32 v40, v26, v27
	v_cvt_pk_bf16_f32 v41, v28, v29
	v_pk_mul_f32 v[32:33], v[32:33], v[36:37] op_sel_hi:[1,0]
	v_pk_fma_f32 v[30:31], v[154:155], v[30:31], v[158:159]
	v_pk_mul_f32 v[28:29], v[28:29], v[36:37] op_sel_hi:[1,0]
	v_pk_mul_f32 v[26:27], v[26:27], v[36:37] op_sel_hi:[1,0]
	v_pk_fma_f32 v[32:33], v[156:157], v[32:33], v[160:161]
	v_pk_fma_f32 v[44:45], v[148:149], v[28:29], v[152:153]
	v_pk_fma_f32 v[28:29], v[146:147], v[26:27], v[150:151]
	v_cvt_pk_bf16_f32 v26, v30, v31
	v_lshlrev_b64 v[30:31], 1, v[42:43]
	v_cvt_pk_bf16_f32 v27, v32, v33
	v_cvt_pk_bf16_f32 v28, v28, v29
	v_cvt_pk_bf16_f32 v29, v44, v45
	v_lshl_add_u64 v[32:33], s[22:23], 0, v[30:31]
	v_lshl_add_u64 v[30:31], s[24:25], 0, v[30:31]
	global_store_dwordx4 v[30:31], v[26:29], off sc1
	s_nop 1
	v_cvt_pk_bf16_f32 v26, v22, v23
	v_cvt_pk_bf16_f32 v27, v24, v25
	v_cvt_pk_bf16_f32 v28, v18, v19
	v_cvt_pk_bf16_f32 v29, v20, v21
	v_pk_mul_f32 v[22:23], v[22:23], v[36:37] op_sel_hi:[1,0]
	v_pk_mul_f32 v[20:21], v[20:21], v[36:37] op_sel_hi:[1,0]
	v_pk_mul_f32 v[18:19], v[18:19], v[36:37] op_sel_hi:[1,0]
	v_pk_mul_f32 v[24:25], v[24:25], v[36:37] op_sel_hi:[1,0]
	v_pk_fma_f32 v[22:23], v[134:135], v[22:23], v[142:143]
	v_pk_fma_f32 v[36:37], v[132:133], v[20:21], v[140:141]
	v_pk_fma_f32 v[20:21], v[130:131], v[18:19], v[138:139]
	v_pk_fma_f32 v[24:25], v[136:137], v[24:25], v[144:145]
	v_cvt_pk_bf16_f32 v18, v22, v23
	v_lshl_add_u64 v[22:23], v[32:33], 0, s[8:9]
	v_cvt_pk_bf16_f32 v19, v24, v25
	v_cvt_pk_bf16_f32 v20, v20, v21
	v_cvt_pk_bf16_f32 v21, v36, v37
	v_lshl_add_u64 v[22:23], v[30:31], 0, s[8:9]
	global_store_dwordx4 v[22:23], v[18:21], off sc1
	s_nop 1
	s_and_b64 vcc, exec, s[6:7]
	s_cbranch_vccnz .LBB0_684
	ds_read_b32 v34, v165 offset:8896
.LBB0_684:
	v_add_u32_e32 v18, 0xb0, v162
	v_ashrrev_i32_e32 v19, 31, v18
	v_lshlrev_b64 v[18:19], 10, v[18:19]
	v_lshl_add_u64 v[22:23], v[18:19], 0, v[210:211]
	v_cvt_pk_bf16_f32 v18, v14, v15
	s_waitcnt lgkmcnt(0)
	v_pk_mul_f32 v[14:15], v[14:15], v[34:35] op_sel_hi:[1,0]
	v_cvt_pk_bf16_f32 v19, v16, v17
	v_cvt_pk_bf16_f32 v20, v10, v11
	v_cvt_pk_bf16_f32 v21, v12, v13
	v_pk_mul_f32 v[16:17], v[16:17], v[34:35] op_sel_hi:[1,0]
	v_pk_fma_f32 v[14:15], v[154:155], v[14:15], v[158:159]
	v_pk_mul_f32 v[12:13], v[12:13], v[34:35] op_sel_hi:[1,0]
	v_pk_mul_f32 v[10:11], v[10:11], v[34:35] op_sel_hi:[1,0]
	v_pk_fma_f32 v[16:17], v[156:157], v[16:17], v[160:161]
	v_pk_fma_f32 v[24:25], v[148:149], v[12:13], v[152:153]
	v_pk_fma_f32 v[12:13], v[146:147], v[10:11], v[150:151]
	v_cvt_pk_bf16_f32 v10, v14, v15
	v_lshlrev_b64 v[14:15], 1, v[22:23]
	v_cvt_pk_bf16_f32 v11, v16, v17
	v_cvt_pk_bf16_f32 v12, v12, v13
	v_cvt_pk_bf16_f32 v13, v24, v25
	v_lshl_add_u64 v[16:17], s[22:23], 0, v[14:15]
	v_lshl_add_u64 v[14:15], s[24:25], 0, v[14:15]
	global_store_dwordx4 v[14:15], v[10:13], off sc1
	s_nop 1
	v_cvt_pk_bf16_f32 v10, v6, v7
	v_cvt_pk_bf16_f32 v11, v8, v9
	v_cvt_pk_bf16_f32 v12, v2, v3
	v_cvt_pk_bf16_f32 v13, v4, v5
	v_pk_mul_f32 v[6:7], v[6:7], v[34:35] op_sel_hi:[1,0]
	v_pk_mul_f32 v[4:5], v[4:5], v[34:35] op_sel_hi:[1,0]
	v_pk_mul_f32 v[2:3], v[2:3], v[34:35] op_sel_hi:[1,0]
	v_pk_mul_f32 v[8:9], v[8:9], v[34:35] op_sel_hi:[1,0]
	v_pk_fma_f32 v[6:7], v[134:135], v[6:7], v[142:143]
	v_pk_fma_f32 v[18:19], v[132:133], v[4:5], v[140:141]
	v_pk_fma_f32 v[4:5], v[130:131], v[2:3], v[138:139]
	v_pk_fma_f32 v[8:9], v[136:137], v[8:9], v[144:145]
	v_cvt_pk_bf16_f32 v2, v6, v7
	v_lshl_add_u64 v[6:7], v[16:17], 0, s[8:9]
	v_cvt_pk_bf16_f32 v3, v8, v9
	v_cvt_pk_bf16_f32 v4, v4, v5
	v_cvt_pk_bf16_f32 v5, v18, v19
	v_lshl_add_u64 v[6:7], v[14:15], 0, s[8:9]
	global_store_dwordx4 v[6:7], v[2:5], off sc1
	s_nop 1
